# v36: byte-phase placement: every 8-byte instruction of the GEMM K-loop (+peel) and of the attention fused loop starts at an address = 0 mod 8 (s_nop pads / e64 widening)
# baseline (speedup 1.0000x reference)
.LBB0_64:
	s_add_i32 s33, s42, 2
	s_nop 0
	s_add_u32 s46, s40, 0x80
	s_addc_u32 s43, s41, 0
	s_nop 0
	s_add_i32 s80, 0, 0x10000
	s_cmp_eq_u32 s84, s42
	s_cselect_b32 s43, s1, s43
	s_cselect_b32 s42, s0, s46
	s_cselect_b32 s47, s75, vcc_hi
	s_cselect_b32 s46, s74, vcc_lo
	s_nop 0
	s_add_i32 s5, 0, 0x14000
	v_add_u32_e32 v140, s80, v185
	v_add_u32_e32 v166, s5, v185
	ds_read_b128 v[128:131], v140
	ds_read_b128 v[132:135], v140 offset:1024
	ds_read_b128 v[136:139], v140 offset:2048
	ds_read_b128 v[140:143], v140 offset:3072
	ds_read_b128 v[144:147], v166
	ds_read_b128 v[148:151], v166 offset:1024
	ds_read_b128 v[152:155], v166 offset:2048
	ds_read_b128 v[166:169], v166 offset:3072
	v_lshl_add_u64 v[182:183], s[40:41], 0, v[162:163]
	s_add_i32 m0, s28, 0xc000
	ds_read_b128 v[170:173], v188
	ds_read_b128 v[174:177], v188 offset:1024
	ds_read_b128 v[178:181], v188 offset:2048
	ds_read_b128 v[214:217], v188 offset:3072
	ds_read_b128 v[218:221], v188 offset:4096
	ds_read_b128 v[222:225], v188 offset:5120
	ds_read_b128 v[226:229], v188 offset:6144
	ds_read_b128 v[230:233], v188 offset:7168
	global_load_lds_dwordx4 v[182:183], off
	v_lshl_add_u64 v[182:183], s[40:41], 0, v[164:165]
	s_add_i32 m0, s28, 0xe000
	s_nop 0
	s_nop 0
	global_load_lds_dwordx4 v[182:183], off
	s_waitcnt vmcnt(8)
	s_waitcnt lgkmcnt(0)
	s_barrier
	s_setprio 1
	s_waitcnt lgkmcnt(0)
	s_nop 0
	v_mfma_f32_16x16x32_bf16 v[124:127], v[128:131], v[170:173], v[124:127]
	v_mfma_f32_16x16x32_bf16 v[120:123], v[136:139], v[170:173], v[120:123]
	v_mfma_f32_16x16x32_bf16 v[108:111], v[128:131], v[178:181], v[108:111]
	v_mfma_f32_16x16x32_bf16 v[104:107], v[136:139], v[178:181], v[104:107]
	v_mfma_f32_16x16x32_bf16 v[92:95], v[128:131], v[218:221], v[92:95]
	v_mfma_f32_16x16x32_bf16 v[88:91], v[136:139], v[218:221], v[88:91]
	v_mfma_f32_16x16x32_bf16 v[76:79], v[128:131], v[226:229], v[76:79]
	v_mfma_f32_16x16x32_bf16 v[72:75], v[136:139], v[226:229], v[72:75]
	v_mfma_f32_16x16x32_bf16 v[124:127], v[132:135], v[174:177], v[124:127]
	v_mfma_f32_16x16x32_bf16 v[120:123], v[140:143], v[174:177], v[120:123]
	v_mfma_f32_16x16x32_bf16 v[108:111], v[132:135], v[214:217], v[108:111]
	v_mfma_f32_16x16x32_bf16 v[104:107], v[140:143], v[214:217], v[104:107]
	v_mfma_f32_16x16x32_bf16 v[92:95], v[132:135], v[222:225], v[92:95]
	v_mfma_f32_16x16x32_bf16 v[88:91], v[140:143], v[222:225], v[88:91]
	v_mfma_f32_16x16x32_bf16 v[76:79], v[132:135], v[230:233], v[76:79]
	v_mfma_f32_16x16x32_bf16 v[72:75], v[140:143], v[230:233], v[72:75]
	s_setprio 0
	s_setprio 1
	v_mfma_f32_16x16x32_bf16 v[116:119], v[144:147], v[170:173], v[116:119]
	v_mfma_f32_16x16x32_bf16 v[112:115], v[152:155], v[170:173], v[112:115]
	v_mfma_f32_16x16x32_bf16 v[100:103], v[144:147], v[178:181], v[100:103]
	v_mfma_f32_16x16x32_bf16 v[96:99], v[152:155], v[178:181], v[96:99]
	v_mfma_f32_16x16x32_bf16 v[84:87], v[144:147], v[218:221], v[84:87]
	v_mfma_f32_16x16x32_bf16 v[80:83], v[152:155], v[218:221], v[80:83]
	v_mfma_f32_16x16x32_bf16 v[68:71], v[144:147], v[226:229], v[68:71]
	v_mfma_f32_16x16x32_bf16 v[64:67], v[152:155], v[226:229], v[64:67]
	v_mfma_f32_16x16x32_bf16 v[116:119], v[148:151], v[174:177], v[116:119]
	v_mfma_f32_16x16x32_bf16 v[112:115], v[166:169], v[174:177], v[112:115]
	v_mfma_f32_16x16x32_bf16 v[100:103], v[148:151], v[214:217], v[100:103]
	v_mfma_f32_16x16x32_bf16 v[96:99], v[166:169], v[214:217], v[96:99]
	v_mfma_f32_16x16x32_bf16 v[84:87], v[148:151], v[222:225], v[84:87]
	v_mfma_f32_16x16x32_bf16 v[80:83], v[166:169], v[222:225], v[80:83]
	v_mfma_f32_16x16x32_bf16 v[68:71], v[148:151], v[230:233], v[68:71]
	v_mfma_f32_16x16x32_bf16 v[64:67], v[166:169], v[230:233], v[64:67]
	s_setprio 0
	s_barrier
	s_add_i32 s80, s80, s27
	s_nop 0
	v_lshl_add_u64 v[182:183], s[46:47], 0, v[192:193]
	s_mov_b32 m0, s80
	s_nop 0
	ds_read_b128 v[170:173], v188 offset:16384
	ds_read_b128 v[174:177], v188 offset:17408
	ds_read_b128 v[178:181], v188 offset:18432
	ds_read_b128 v[214:217], v188 offset:19456
	ds_read_b128 v[218:221], v188 offset:20480
	ds_read_b128 v[222:225], v188 offset:21504
	ds_read_b128 v[226:229], v188 offset:22528
	ds_read_b128 v[230:233], v188 offset:23552
	global_load_lds_dwordx4 v[182:183], off
	s_add_i32 m0, s80, 0x2000
	v_lshl_add_u64 v[190:191], s[46:47], 0, v[160:161]
	s_add_u32 s46, s46, s30
	s_addc_u32 s47, s47, 0
	s_add_i32 s5, s5, s27
	s_nop 0
	global_load_lds_dwordx4 v[190:191], off
	v_lshl_add_u64 v[200:201], s[46:47], 0, v[192:193]
	s_mov_b32 m0, s5
	s_nop 0
	v_lshl_add_u64 v[234:235], s[46:47], 0, v[160:161]
	global_load_lds_dwordx4 v[200:201], off
	s_add_i32 m0, s5, 0x2000
	v_lshl_add_u64 v[236:237], s[42:43], 0, v[156:157]
	global_load_lds_dwordx4 v[234:235], off
	s_mov_b32 m0, s28
	s_nop 0
	v_lshl_add_u64 v[238:239], s[42:43], 0, v[158:159]
	global_load_lds_dwordx4 v[236:237], off
	s_mov_b32 m0, s69
	s_nop 0
	global_load_lds_dwordx4 v[238:239], off
	s_waitcnt vmcnt(8)
	s_waitcnt lgkmcnt(0)
	s_barrier
	s_setprio 1
	s_waitcnt lgkmcnt(0)
	s_nop 0
	v_mfma_f32_16x16x32_bf16 v[60:63], v[128:131], v[170:173], v[60:63]
	v_mfma_f32_16x16x32_bf16 v[56:59], v[136:139], v[170:173], v[56:59]
	v_mfma_f32_16x16x32_bf16 v[44:47], v[128:131], v[178:181], v[44:47]
	v_mfma_f32_16x16x32_bf16 v[40:43], v[136:139], v[178:181], v[40:43]
	v_mfma_f32_16x16x32_bf16 v[28:31], v[128:131], v[218:221], v[28:31]
	v_mfma_f32_16x16x32_bf16 v[24:27], v[136:139], v[218:221], v[24:27]
	v_mfma_f32_16x16x32_bf16 v[12:15], v[128:131], v[226:229], v[12:15]
	v_mfma_f32_16x16x32_bf16 v[8:11], v[136:139], v[226:229], v[8:11]
	v_mfma_f32_16x16x32_bf16 v[60:63], v[132:135], v[174:177], v[60:63]
	v_mfma_f32_16x16x32_bf16 v[56:59], v[140:143], v[174:177], v[56:59]
	v_mfma_f32_16x16x32_bf16 v[44:47], v[132:135], v[214:217], v[44:47]
	v_mfma_f32_16x16x32_bf16 v[40:43], v[140:143], v[214:217], v[40:43]
	v_mfma_f32_16x16x32_bf16 v[28:31], v[132:135], v[222:225], v[28:31]
	v_mfma_f32_16x16x32_bf16 v[24:27], v[140:143], v[222:225], v[24:27]
	v_mfma_f32_16x16x32_bf16 v[12:15], v[132:135], v[230:233], v[12:15]
	v_mfma_f32_16x16x32_bf16 v[8:11], v[140:143], v[230:233], v[8:11]
	s_setprio 0
	s_setprio 1
	v_mfma_f32_16x16x32_bf16 v[52:55], v[144:147], v[170:173], v[52:55]
	v_mfma_f32_16x16x32_bf16 v[48:51], v[152:155], v[170:173], v[48:51]
	v_mfma_f32_16x16x32_bf16 v[36:39], v[144:147], v[178:181], v[36:39]
	v_mfma_f32_16x16x32_bf16 v[32:35], v[152:155], v[178:181], v[32:35]
	v_mfma_f32_16x16x32_bf16 v[20:23], v[144:147], v[218:221], v[20:23]
	v_mfma_f32_16x16x32_bf16 v[16:19], v[152:155], v[218:221], v[16:19]
	v_mfma_f32_16x16x32_bf16 v[4:7], v[144:147], v[226:229], v[4:7]
	v_mfma_f32_16x16x32_bf16 v[0:3], v[152:155], v[226:229], v[0:3]
	v_mfma_f32_16x16x32_bf16 v[52:55], v[148:151], v[174:177], v[52:55]
	v_mfma_f32_16x16x32_bf16 v[48:51], v[166:169], v[174:177], v[48:51]
	v_mfma_f32_16x16x32_bf16 v[36:39], v[148:151], v[214:217], v[36:39]
	v_mfma_f32_16x16x32_bf16 v[32:35], v[166:169], v[214:217], v[32:35]
	v_mfma_f32_16x16x32_bf16 v[20:23], v[148:151], v[222:225], v[20:23]
	v_mfma_f32_16x16x32_bf16 v[16:19], v[166:169], v[222:225], v[16:19]
	v_mfma_f32_16x16x32_bf16 v[4:7], v[148:151], v[230:233], v[4:7]
	v_mfma_f32_16x16x32_bf16 v[0:3], v[166:169], v[230:233], v[0:3]
	s_setprio 0
	s_barrier
.Lmy_sp3:
	s_add_i32 s5, 0, 0x18000
	s_add_i32 s46, 0, 0x1c000
	v_add_u32_e32 v140, s5, v185
	v_add_u32_e32 v166, s46, v185
	ds_read_b128 v[128:131], v140
	ds_read_b128 v[132:135], v140 offset:1024
	ds_read_b128 v[136:139], v140 offset:2048
	ds_read_b128 v[140:143], v140 offset:3072
	ds_read_b128 v[144:147], v166
	ds_read_b128 v[148:151], v166 offset:1024
	ds_read_b128 v[152:155], v166 offset:2048
	ds_read_b128 v[166:169], v166 offset:3072
	s_add_u32 s42, s42, s30
	s_addc_u32 s43, s43, 0
	s_mov_b32 m0, s72
	s_nop 0
	v_lshl_add_u64 v[240:241], s[42:43], 0, v[156:157]
	ds_read_b128 v[170:173], v188 offset:32768
	ds_read_b128 v[174:177], v188 offset:33792
	ds_read_b128 v[178:181], v188 offset:34816
	ds_read_b128 v[214:217], v188 offset:35840
	ds_read_b128 v[218:221], v188 offset:36864
	ds_read_b128 v[222:225], v188 offset:37888
	ds_read_b128 v[226:229], v188 offset:38912
	ds_read_b128 v[230:233], v188 offset:39936
	global_load_lds_dwordx4 v[240:241], off
	v_lshl_add_u64 v[240:241], s[42:43], 0, v[158:159]
	s_mov_b32 m0, s76
	s_nop 0
	global_load_lds_dwordx4 v[240:241], off
	s_waitcnt vmcnt(8)
	s_waitcnt lgkmcnt(0)
	s_barrier
	s_setprio 1
	s_waitcnt lgkmcnt(0)
	s_nop 0
	v_mfma_f32_16x16x32_bf16 v[124:127], v[128:131], v[170:173], v[124:127]
	v_mfma_f32_16x16x32_bf16 v[120:123], v[136:139], v[170:173], v[120:123]
	v_mfma_f32_16x16x32_bf16 v[108:111], v[128:131], v[178:181], v[108:111]
	v_mfma_f32_16x16x32_bf16 v[104:107], v[136:139], v[178:181], v[104:107]
	v_mfma_f32_16x16x32_bf16 v[92:95], v[128:131], v[218:221], v[92:95]
	v_mfma_f32_16x16x32_bf16 v[88:91], v[136:139], v[218:221], v[88:91]
	v_mfma_f32_16x16x32_bf16 v[76:79], v[128:131], v[226:229], v[76:79]
	v_mfma_f32_16x16x32_bf16 v[72:75], v[136:139], v[226:229], v[72:75]
	v_mfma_f32_16x16x32_bf16 v[124:127], v[132:135], v[174:177], v[124:127]
	v_mfma_f32_16x16x32_bf16 v[120:123], v[140:143], v[174:177], v[120:123]
	v_mfma_f32_16x16x32_bf16 v[108:111], v[132:135], v[214:217], v[108:111]
	v_mfma_f32_16x16x32_bf16 v[104:107], v[140:143], v[214:217], v[104:107]
	v_mfma_f32_16x16x32_bf16 v[92:95], v[132:135], v[222:225], v[92:95]
	v_mfma_f32_16x16x32_bf16 v[88:91], v[140:143], v[222:225], v[88:91]
	v_mfma_f32_16x16x32_bf16 v[76:79], v[132:135], v[230:233], v[76:79]
	v_mfma_f32_16x16x32_bf16 v[72:75], v[140:143], v[230:233], v[72:75]
	s_setprio 0
	s_setprio 1
	v_mfma_f32_16x16x32_bf16 v[116:119], v[144:147], v[170:173], v[116:119]
	v_mfma_f32_16x16x32_bf16 v[112:115], v[152:155], v[170:173], v[112:115]
	v_mfma_f32_16x16x32_bf16 v[100:103], v[144:147], v[178:181], v[100:103]
	v_mfma_f32_16x16x32_bf16 v[96:99], v[152:155], v[178:181], v[96:99]
	v_mfma_f32_16x16x32_bf16 v[84:87], v[144:147], v[218:221], v[84:87]
	v_mfma_f32_16x16x32_bf16 v[80:83], v[152:155], v[218:221], v[80:83]
	v_mfma_f32_16x16x32_bf16 v[68:71], v[144:147], v[226:229], v[68:71]
	v_mfma_f32_16x16x32_bf16 v[64:67], v[152:155], v[226:229], v[64:67]
	v_mfma_f32_16x16x32_bf16 v[116:119], v[148:151], v[174:177], v[116:119]
	v_mfma_f32_16x16x32_bf16 v[112:115], v[166:169], v[174:177], v[112:115]
	v_mfma_f32_16x16x32_bf16 v[100:103], v[148:151], v[214:217], v[100:103]
	v_mfma_f32_16x16x32_bf16 v[96:99], v[166:169], v[214:217], v[96:99]
	v_mfma_f32_16x16x32_bf16 v[84:87], v[148:151], v[222:225], v[84:87]
	v_mfma_f32_16x16x32_bf16 v[80:83], v[166:169], v[222:225], v[80:83]
	v_mfma_f32_16x16x32_bf16 v[68:71], v[148:151], v[230:233], v[68:71]
	v_mfma_f32_16x16x32_bf16 v[64:67], v[166:169], v[230:233], v[64:67]
	s_setprio 0
	s_barrier
	s_add_i32 s5, s5, s27
	s_nop 0
	v_lshl_add_u64 v[182:183], v[182:183], 0, s[70:71]
	s_mov_b32 m0, s5
	s_nop 0
	ds_read_b128 v[170:173], v188 offset:49152
	ds_read_b128 v[174:177], v188 offset:50176
	ds_read_b128 v[178:181], v188 offset:51200
	ds_read_b128 v[214:217], v188 offset:52224
	ds_read_b128 v[218:221], v188 offset:53248
	ds_read_b128 v[222:225], v188 offset:54272
	ds_read_b128 v[226:229], v188 offset:55296
	ds_read_b128 v[230:233], v188 offset:56320
	global_load_lds_dwordx4 v[182:183], off
	v_lshl_add_u64 v[182:183], v[190:191], 0, s[70:71]
	s_add_i32 m0, s5, 0x2000
	s_add_i32 s5, s46, s27
	s_nop 0
	global_load_lds_dwordx4 v[182:183], off
	v_lshl_add_u64 v[182:183], v[200:201], 0, s[70:71]
	s_mov_b32 m0, s5
	s_nop 0
	global_load_lds_dwordx4 v[182:183], off
	v_lshl_add_u64 v[182:183], v[234:235], 0, s[70:71]
	s_add_i32 m0, s5, 0x2000
	s_nop 0
	s_nop 0
	global_load_lds_dwordx4 v[182:183], off
	v_lshl_add_u64 v[182:183], v[236:237], 0, s[70:71]
	s_mov_b32 m0, s81
	s_nop 0
	global_load_lds_dwordx4 v[182:183], off
	v_lshl_add_u64 v[182:183], v[238:239], 0, s[70:71]
	s_mov_b32 m0, s82
	s_nop 0
	global_load_lds_dwordx4 v[182:183], off
	s_waitcnt vmcnt(8)
	s_waitcnt lgkmcnt(0)
	s_barrier
	s_setprio 1
	s_waitcnt lgkmcnt(0)
	s_nop 0
	v_mfma_f32_16x16x32_bf16 v[60:63], v[128:131], v[170:173], v[60:63]
	v_mfma_f32_16x16x32_bf16 v[56:59], v[136:139], v[170:173], v[56:59]
	v_mfma_f32_16x16x32_bf16 v[44:47], v[128:131], v[178:181], v[44:47]
	v_mfma_f32_16x16x32_bf16 v[40:43], v[136:139], v[178:181], v[40:43]
	v_mfma_f32_16x16x32_bf16 v[28:31], v[128:131], v[218:221], v[28:31]
	v_mfma_f32_16x16x32_bf16 v[24:27], v[136:139], v[218:221], v[24:27]
	v_mfma_f32_16x16x32_bf16 v[12:15], v[128:131], v[226:229], v[12:15]
	v_mfma_f32_16x16x32_bf16 v[8:11], v[136:139], v[226:229], v[8:11]
	v_mfma_f32_16x16x32_bf16 v[60:63], v[132:135], v[174:177], v[60:63]
	v_mfma_f32_16x16x32_bf16 v[56:59], v[140:143], v[174:177], v[56:59]
	v_mfma_f32_16x16x32_bf16 v[44:47], v[132:135], v[214:217], v[44:47]
	v_mfma_f32_16x16x32_bf16 v[40:43], v[140:143], v[214:217], v[40:43]
	v_mfma_f32_16x16x32_bf16 v[28:31], v[132:135], v[222:225], v[28:31]
	v_mfma_f32_16x16x32_bf16 v[24:27], v[140:143], v[222:225], v[24:27]
	v_mfma_f32_16x16x32_bf16 v[12:15], v[132:135], v[230:233], v[12:15]
	v_mfma_f32_16x16x32_bf16 v[8:11], v[140:143], v[230:233], v[8:11]
	s_setprio 0
	s_setprio 1
	v_mfma_f32_16x16x32_bf16 v[52:55], v[144:147], v[170:173], v[52:55]
	v_mfma_f32_16x16x32_bf16 v[48:51], v[152:155], v[170:173], v[48:51]
	v_mfma_f32_16x16x32_bf16 v[36:39], v[144:147], v[178:181], v[36:39]
	v_mfma_f32_16x16x32_bf16 v[32:35], v[152:155], v[178:181], v[32:35]
	v_mfma_f32_16x16x32_bf16 v[20:23], v[144:147], v[218:221], v[20:23]
	v_mfma_f32_16x16x32_bf16 v[16:19], v[152:155], v[218:221], v[16:19]
	v_mfma_f32_16x16x32_bf16 v[4:7], v[144:147], v[226:229], v[4:7]
	v_mfma_f32_16x16x32_bf16 v[0:3], v[152:155], v[226:229], v[0:3]
	v_mfma_f32_16x16x32_bf16 v[52:55], v[148:151], v[174:177], v[52:55]
	v_mfma_f32_16x16x32_bf16 v[48:51], v[166:169], v[174:177], v[48:51]
	v_mfma_f32_16x16x32_bf16 v[36:39], v[148:151], v[214:217], v[36:39]
	v_mfma_f32_16x16x32_bf16 v[32:35], v[166:169], v[214:217], v[32:35]
	v_mfma_f32_16x16x32_bf16 v[20:23], v[148:151], v[222:225], v[20:23]
	v_mfma_f32_16x16x32_bf16 v[16:19], v[166:169], v[222:225], v[16:19]
	v_mfma_f32_16x16x32_bf16 v[4:7], v[148:151], v[230:233], v[4:7]
	v_mfma_f32_16x16x32_bf16 v[0:3], v[166:169], v[230:233], v[0:3]
	s_setprio 0
	s_barrier
	s_add_u32 s40, s40, 0x100
	s_addc_u32 s41, s41, 0
	s_nop 0
	s_add_u32 vcc_lo, vcc_lo, 0x100
	s_addc_u32 vcc_hi, vcc_hi, 0
	s_cmp_ge_u32 s33, s78
	s_mov_b32 s42, s33
	s_cbranch_scc0 .LBB0_64
	s_and_b64 vcc, exec, s[66:67]
	s_cbranch_vccz .LBB0_67
	s_barrier

.Lmy_peel:
	s_add_i32 s33, s42, 2
	s_nop 0
	s_add_u32 s46, s40, 0x80
	s_addc_u32 s43, s41, 0
	s_nop 0
	s_add_i32 s80, 0, 0x10000
	s_cmp_eq_u32 s84, s42
	s_cselect_b32 s43, s1, s43
	s_cselect_b32 s42, s0, s46
	s_cselect_b32 s47, s75, vcc_hi
	s_cselect_b32 s46, s74, vcc_lo
	s_nop 0
	s_add_i32 s5, 0, 0x14000
	v_add_u32_e32 v140, s80, v185
	v_add_u32_e32 v166, s5, v185
	ds_read_b128 v[128:131], v140
	ds_read_b128 v[132:135], v140 offset:1024
	ds_read_b128 v[136:139], v140 offset:2048
	ds_read_b128 v[140:143], v140 offset:3072
	ds_read_b128 v[144:147], v166
	ds_read_b128 v[148:151], v166 offset:1024
	ds_read_b128 v[152:155], v166 offset:2048
	ds_read_b128 v[166:169], v166 offset:3072
	v_lshl_add_u64 v[182:183], s[40:41], 0, v[162:163]
	s_add_i32 m0, s28, 0xc000
	ds_read_b128 v[170:173], v188
	ds_read_b128 v[174:177], v188 offset:1024
	ds_read_b128 v[178:181], v188 offset:2048
	ds_read_b128 v[214:217], v188 offset:3072
	ds_read_b128 v[218:221], v188 offset:4096
	ds_read_b128 v[222:225], v188 offset:5120
	ds_read_b128 v[226:229], v188 offset:6144
	ds_read_b128 v[230:233], v188 offset:7168
	global_load_lds_dwordx4 v[182:183], off
	v_lshl_add_u64 v[182:183], s[40:41], 0, v[164:165]
	s_add_i32 m0, s28, 0xe000
	s_nop 0
	s_nop 0
	global_load_lds_dwordx4 v[182:183], off
	s_waitcnt vmcnt(24)
	s_waitcnt lgkmcnt(0)
	s_barrier
	s_setprio 1
	s_waitcnt lgkmcnt(0)
	s_nop 0
	v_mfma_f32_16x16x32_bf16 v[124:127], v[128:131], v[170:173], v[124:127]
	v_mfma_f32_16x16x32_bf16 v[120:123], v[136:139], v[170:173], v[120:123]
	v_mfma_f32_16x16x32_bf16 v[108:111], v[128:131], v[178:181], v[108:111]
	v_mfma_f32_16x16x32_bf16 v[104:107], v[136:139], v[178:181], v[104:107]
	v_mfma_f32_16x16x32_bf16 v[92:95], v[128:131], v[218:221], v[92:95]
	v_mfma_f32_16x16x32_bf16 v[88:91], v[136:139], v[218:221], v[88:91]
	v_mfma_f32_16x16x32_bf16 v[76:79], v[128:131], v[226:229], v[76:79]
	v_mfma_f32_16x16x32_bf16 v[72:75], v[136:139], v[226:229], v[72:75]
	v_mfma_f32_16x16x32_bf16 v[124:127], v[132:135], v[174:177], v[124:127]
	v_mfma_f32_16x16x32_bf16 v[120:123], v[140:143], v[174:177], v[120:123]
	v_mfma_f32_16x16x32_bf16 v[108:111], v[132:135], v[214:217], v[108:111]
	v_mfma_f32_16x16x32_bf16 v[104:107], v[140:143], v[214:217], v[104:107]
	v_mfma_f32_16x16x32_bf16 v[92:95], v[132:135], v[222:225], v[92:95]
	v_mfma_f32_16x16x32_bf16 v[88:91], v[140:143], v[222:225], v[88:91]
	v_mfma_f32_16x16x32_bf16 v[76:79], v[132:135], v[230:233], v[76:79]
	v_mfma_f32_16x16x32_bf16 v[72:75], v[140:143], v[230:233], v[72:75]
	s_setprio 0
	s_setprio 1
	v_mfma_f32_16x16x32_bf16 v[116:119], v[144:147], v[170:173], v[116:119]
	v_mfma_f32_16x16x32_bf16 v[112:115], v[152:155], v[170:173], v[112:115]
	v_mfma_f32_16x16x32_bf16 v[100:103], v[144:147], v[178:181], v[100:103]
	v_mfma_f32_16x16x32_bf16 v[96:99], v[152:155], v[178:181], v[96:99]
	v_mfma_f32_16x16x32_bf16 v[84:87], v[144:147], v[218:221], v[84:87]
	v_mfma_f32_16x16x32_bf16 v[80:83], v[152:155], v[218:221], v[80:83]
	v_mfma_f32_16x16x32_bf16 v[68:71], v[144:147], v[226:229], v[68:71]
	v_mfma_f32_16x16x32_bf16 v[64:67], v[152:155], v[226:229], v[64:67]
	v_mfma_f32_16x16x32_bf16 v[116:119], v[148:151], v[174:177], v[116:119]
	v_mfma_f32_16x16x32_bf16 v[112:115], v[166:169], v[174:177], v[112:115]
	v_mfma_f32_16x16x32_bf16 v[100:103], v[148:151], v[214:217], v[100:103]
	v_mfma_f32_16x16x32_bf16 v[96:99], v[166:169], v[214:217], v[96:99]
	v_mfma_f32_16x16x32_bf16 v[84:87], v[148:151], v[222:225], v[84:87]
	v_mfma_f32_16x16x32_bf16 v[80:83], v[166:169], v[222:225], v[80:83]
	v_mfma_f32_16x16x32_bf16 v[68:71], v[148:151], v[230:233], v[68:71]
	v_mfma_f32_16x16x32_bf16 v[64:67], v[166:169], v[230:233], v[64:67]
	s_setprio 0
	s_barrier
	s_add_i32 s80, s80, s27
	s_nop 0
	v_lshl_add_u64 v[182:183], s[46:47], 0, v[192:193]
	s_mov_b32 m0, s80
	s_nop 0
	ds_read_b128 v[170:173], v188 offset:16384
	ds_read_b128 v[174:177], v188 offset:17408
	ds_read_b128 v[178:181], v188 offset:18432
	ds_read_b128 v[214:217], v188 offset:19456
	ds_read_b128 v[218:221], v188 offset:20480
	ds_read_b128 v[222:225], v188 offset:21504
	ds_read_b128 v[226:229], v188 offset:22528
	ds_read_b128 v[230:233], v188 offset:23552
	global_load_lds_dwordx4 v[182:183], off
	s_add_i32 m0, s80, 0x2000
	v_lshl_add_u64 v[190:191], s[46:47], 0, v[160:161]
	s_add_u32 s46, s46, s30
	s_addc_u32 s47, s47, 0
	s_add_i32 s5, s5, s27
	s_nop 0
	global_load_lds_dwordx4 v[190:191], off
	v_lshl_add_u64 v[200:201], s[46:47], 0, v[192:193]
	s_mov_b32 m0, s5
	s_nop 0
	v_lshl_add_u64 v[234:235], s[46:47], 0, v[160:161]
	global_load_lds_dwordx4 v[200:201], off
	s_add_i32 m0, s5, 0x2000
	v_lshl_add_u64 v[236:237], s[42:43], 0, v[156:157]
	global_load_lds_dwordx4 v[234:235], off
	s_mov_b32 m0, s28
	s_nop 0
	v_lshl_add_u64 v[238:239], s[42:43], 0, v[158:159]
	global_load_lds_dwordx4 v[236:237], off
	s_mov_b32 m0, s69
	s_nop 0
	global_load_lds_dwordx4 v[238:239], off
	s_waitcnt vmcnt(24)
	s_waitcnt lgkmcnt(0)
	s_barrier
	s_setprio 1
	s_waitcnt lgkmcnt(0)
	s_nop 0
	v_mfma_f32_16x16x32_bf16 v[60:63], v[128:131], v[170:173], v[60:63]
	v_mfma_f32_16x16x32_bf16 v[56:59], v[136:139], v[170:173], v[56:59]
	v_mfma_f32_16x16x32_bf16 v[44:47], v[128:131], v[178:181], v[44:47]
	v_mfma_f32_16x16x32_bf16 v[40:43], v[136:139], v[178:181], v[40:43]
	v_mfma_f32_16x16x32_bf16 v[28:31], v[128:131], v[218:221], v[28:31]
	v_mfma_f32_16x16x32_bf16 v[24:27], v[136:139], v[218:221], v[24:27]
	v_mfma_f32_16x16x32_bf16 v[12:15], v[128:131], v[226:229], v[12:15]
	v_mfma_f32_16x16x32_bf16 v[8:11], v[136:139], v[226:229], v[8:11]
	v_mfma_f32_16x16x32_bf16 v[60:63], v[132:135], v[174:177], v[60:63]
	v_mfma_f32_16x16x32_bf16 v[56:59], v[140:143], v[174:177], v[56:59]
	v_mfma_f32_16x16x32_bf16 v[44:47], v[132:135], v[214:217], v[44:47]
	v_mfma_f32_16x16x32_bf16 v[40:43], v[140:143], v[214:217], v[40:43]
	v_mfma_f32_16x16x32_bf16 v[28:31], v[132:135], v[222:225], v[28:31]
	v_mfma_f32_16x16x32_bf16 v[24:27], v[140:143], v[222:225], v[24:27]
	v_mfma_f32_16x16x32_bf16 v[12:15], v[132:135], v[230:233], v[12:15]
	v_mfma_f32_16x16x32_bf16 v[8:11], v[140:143], v[230:233], v[8:11]
	s_setprio 0
	s_setprio 1
	v_mfma_f32_16x16x32_bf16 v[52:55], v[144:147], v[170:173], v[52:55]
	v_mfma_f32_16x16x32_bf16 v[48:51], v[152:155], v[170:173], v[48:51]
	v_mfma_f32_16x16x32_bf16 v[36:39], v[144:147], v[178:181], v[36:39]
	v_mfma_f32_16x16x32_bf16 v[32:35], v[152:155], v[178:181], v[32:35]
	v_mfma_f32_16x16x32_bf16 v[20:23], v[144:147], v[218:221], v[20:23]
	v_mfma_f32_16x16x32_bf16 v[16:19], v[152:155], v[218:221], v[16:19]
	v_mfma_f32_16x16x32_bf16 v[4:7], v[144:147], v[226:229], v[4:7]
	v_mfma_f32_16x16x32_bf16 v[0:3], v[152:155], v[226:229], v[0:3]
	v_mfma_f32_16x16x32_bf16 v[52:55], v[148:151], v[174:177], v[52:55]
	v_mfma_f32_16x16x32_bf16 v[48:51], v[166:169], v[174:177], v[48:51]
	v_mfma_f32_16x16x32_bf16 v[36:39], v[148:151], v[214:217], v[36:39]
	v_mfma_f32_16x16x32_bf16 v[32:35], v[166:169], v[214:217], v[32:35]
	v_mfma_f32_16x16x32_bf16 v[20:23], v[148:151], v[222:225], v[20:23]
	v_mfma_f32_16x16x32_bf16 v[16:19], v[166:169], v[222:225], v[16:19]
	v_mfma_f32_16x16x32_bf16 v[4:7], v[148:151], v[230:233], v[4:7]
	v_mfma_f32_16x16x32_bf16 v[0:3], v[166:169], v[230:233], v[0:3]
	s_setprio 0
	s_barrier
	s_branch .Lmy_sp3

.Lat_loop:
	v_add_u32_e32 v188, s12, v157
	v_add_u32_e32 v189, s12, v158
	v_add_u32_e32 v222, s12, v159
	v_add_u32_e64 v223, s12, v160
	s_cmp_ge_i32 s5, s81
	s_cbranch_scc1 .Lat_rare_8
	s_waitcnt lgkmcnt(8)
	v_mfma_f32_32x32x16_bf16 v[0:15], v[224:227], v[114:117], v[0:15]
	v_exp_f32_e32 v82, v82
	v_exp_f32_e32 v83, v83
	ds_read_b64_tr_b16 v[224:225], v215 offset:8192
	ds_read_b64_tr_b16 v[226:227], v215 offset:10240
	v_mfma_f32_32x32x16_bf16 v[16:31], v[228:231], v[114:117], v[16:31]
	v_exp_f32_e32 v84, v84
	v_exp_f32_e32 v85, v85
	v_add_f32_e64 v180, v82, v83
	ds_read_b64_tr_b16 v[228:229], v165 offset:8192
	ds_read_b64_tr_b16 v[230:231], v165 offset:10240
	v_mfma_f32_32x32x16_bf16 v[32:47], v[232:235], v[114:117], v[32:47]
	v_exp_f32_e32 v86, v86
	v_exp_f32_e32 v87, v87
	v_add_f32_e32 v180, v180, v84
	v_add_f32_e32 v180, v180, v85
	ds_read_b64_tr_b16 v[232:233], v216 offset:8192
	ds_read_b64_tr_b16 v[234:235], v216 offset:10240
	v_mfma_f32_32x32x16_bf16 v[48:63], v[236:239], v[114:117], v[48:63]
	v_exp_f32_e32 v88, v88
	v_exp_f32_e32 v89, v89
	v_add_f32_e32 v180, v180, v86
	v_add_f32_e32 v180, v180, v87
	ds_read_b64_tr_b16 v[236:237], v217 offset:8192
	ds_read_b64_tr_b16 v[238:239], v217 offset:10240
	s_waitcnt lgkmcnt(8)
	s_nop 0
	v_mfma_f32_32x32x16_bf16 v[0:15], v[240:243], v[118:121], v[0:15]
	v_exp_f32_e32 v90, v90
	v_exp_f32_e32 v91, v91
	v_add_f32_e64 v180, v180, v88
	v_cvt_pk_bf16_f32 v114, v82, v83
	ds_read_b64_tr_b16 v[240:241], v215 offset:12288
	ds_read_b64_tr_b16 v[242:243], v215 offset:14336
	v_mfma_f32_32x32x16_bf16 v[16:31], v[130:133], v[118:121], v[16:31]
	v_exp_f32_e32 v92, v92
	v_exp_f32_e32 v93, v93
	v_add_f32_e64 v180, v180, v89
	v_cvt_pk_bf16_f32 v115, v84, v85
	ds_read_b64_tr_b16 v[130:131], v165 offset:12288
	ds_read_b64_tr_b16 v[132:133], v165 offset:14336
	v_mfma_f32_32x32x16_bf16 v[32:47], v[134:137], v[118:121], v[32:47]
	v_exp_f32_e32 v94, v94
	v_exp_f32_e32 v95, v95
	v_add_f32_e64 v180, v180, v90
	v_cvt_pk_bf16_f32 v116, v86, v87
	ds_read_b64_tr_b16 v[134:135], v216 offset:12288
	ds_read_b64_tr_b16 v[136:137], v216 offset:14336
	v_mfma_f32_32x32x16_bf16 v[48:63], v[184:187], v[118:121], v[48:63]
	v_exp_f32_e32 v96, v96
	v_exp_f32_e32 v97, v97
	v_add_f32_e64 v180, v180, v91
	v_cvt_pk_bf16_f32 v117, v88, v89
	ds_read_b64_tr_b16 v[184:185], v217 offset:12288
	ds_read_b64_tr_b16 v[186:187], v217 offset:14336
	s_waitcnt lgkmcnt(8)
	s_nop 0
	v_mfma_f32_32x32x16_bf16 v[0:15], v[224:227], v[122:125], v[0:15]
	v_exp_f32_e32 v98, v98
	v_exp_f32_e32 v99, v99
	v_add_f32_e64 v180, v180, v92
	v_cvt_pk_bf16_f32 v118, v90, v91
	v_mfma_f32_32x32x16_bf16 v[16:31], v[228:231], v[122:125], v[16:31]
	v_exp_f32_e32 v100, v100
	v_exp_f32_e32 v101, v101
	v_add_f32_e64 v180, v180, v93
	v_cvt_pk_bf16_f32 v119, v92, v93
	v_mfma_f32_32x32x16_bf16 v[32:47], v[232:235], v[122:125], v[32:47]
	v_exp_f32_e32 v102, v102
	v_exp_f32_e32 v103, v103
	v_add_f32_e64 v180, v180, v94
	v_cvt_pk_bf16_f32 v120, v94, v95
	v_mfma_f32_32x32x16_bf16 v[48:63], v[236:239], v[122:125], v[48:63]
	v_exp_f32_e32 v104, v104
	v_exp_f32_e32 v105, v105
	v_add_f32_e64 v180, v180, v95
	v_cvt_pk_bf16_f32 v121, v96, v97
	ds_read_b128 v[224:227], v188
	ds_read_b128 v[228:231], v189
	ds_read_b128 v[232:235], v222
	ds_read_b128 v[236:239], v223
	s_waitcnt lgkmcnt(4)
	s_nop 0
	v_mfma_f32_32x32x16_bf16 v[0:15], v[240:243], v[126:129], v[0:15]
	v_exp_f32_e32 v106, v106
	v_exp_f32_e32 v107, v107
	v_add_f32_e32 v180, v180, v96
	v_add_f32_e32 v180, v180, v97
	v_mfma_f32_32x32x16_bf16 v[16:31], v[130:133], v[126:129], v[16:31]
	v_exp_f32_e32 v108, v108
	v_exp_f32_e32 v109, v109
	v_add_f32_e32 v180, v180, v98
	v_add_f32_e32 v180, v180, v99
	v_mfma_f32_32x32x16_bf16 v[32:47], v[134:137], v[126:129], v[32:47]
	v_exp_f32_e32 v110, v110
	v_exp_f32_e32 v111, v111
	v_add_f32_e32 v180, v180, v100
	v_add_f32_e32 v180, v180, v101
	v_mfma_f32_32x32x16_bf16 v[48:63], v[184:187], v[126:129], v[48:63]
	v_exp_f32_e32 v112, v112
	v_exp_f32_e32 v113, v113
	v_add_f32_e32 v180, v180, v102
	v_add_f32_e32 v180, v180, v103
	ds_read_b128 v[240:243], v188 offset:4096
	ds_read_b128 v[130:133], v189 offset:4096
	ds_read_b128 v[134:137], v222 offset:4096
	ds_read_b128 v[184:187], v223 offset:4096
	s_waitcnt lgkmcnt(4)
	s_nop 0
	v_mfma_f32_32x32x16_bf16 v[82:97], v[224:227], v[150:153], v[64:79]
	v_add_f32_e32 v180, v180, v104
	v_add_f32_e32 v180, v180, v105
	v_add_f32_e64 v180, v180, v106
	v_cvt_pk_bf16_f32 v122, v98, v99
	v_cvt_pk_bf16_f32 v123, v100, v101
	s_add_i32 m0, s13, s68
	s_nop 0
	global_load_lds_dwordx4 v154, s[14:15]
	v_mfma_f32_32x32x16_bf16 v[82:97], v[228:231], v[146:149], v[82:97]
	v_add_f32_e32 v180, v180, v107
	v_add_f32_e32 v180, v180, v108
	v_add_f32_e64 v180, v180, v109
	v_cvt_pk_bf16_f32 v124, v102, v103
	v_cvt_pk_bf16_f32 v125, v104, v105
	s_add_i32 m0, s17, s69
	s_nop 0
	global_load_lds_dwordx4 v155, s[18:19]
	v_mfma_f32_32x32x16_bf16 v[82:97], v[232:235], v[142:145], v[82:97]
	v_add_f32_e32 v180, v180, v110
	v_add_f32_e32 v180, v180, v111
	v_cvt_pk_bf16_f32 v126, v106, v107
	v_cvt_pk_bf16_f32 v127, v108, v109
	s_add_i32 m0, m0, 0x400
	s_nop 0
	s_nop 0
	global_load_lds_dwordx4 v156, s[18:19]
	v_mfma_f32_32x32x16_bf16 v[82:97], v[236:239], v[138:141], v[82:97]
	v_add_f32_e32 v180, v180, v112
	v_add_f32_e32 v180, v180, v113
	v_cvt_pk_bf16_f32 v128, v110, v111
	v_cvt_pk_bf16_f32 v129, v112, v113
	v_cmp_ngt_f32_e64 vcc, s23, v180
	s_add_i32 s12, s12, 8192
	s_cmp_eq_u32 s12, 32768
	s_cselect_b32 s12, 0, s12
	s_nop 0
	s_add_i32 s84, s84, 16384
	s_cmp_eq_u32 s84, 114688
	s_cselect_b32 s84, 32768, s84
	s_waitcnt lgkmcnt(0)
	s_nop 0
	v_mfma_f32_32x32x16_bf16 v[98:113], v[240:243], v[150:153], v[64:79]
	v_add_u32_e32 v215, s84, v161
	v_add_u32_e32 v165, s84, v162
	v_add_u32_e32 v216, s84, v163
	v_add_u32_e32 v217, s84, v164
	ds_read_b64_tr_b16 v[224:225], v215 offset:0
	ds_read_b64_tr_b16 v[226:227], v215 offset:2048
	s_add_i32 s13, s13, 8192
	s_cmp_eq_u32 s13, 32768
	s_cselect_b32 s13, 0, s13
	s_nop 0
	v_mfma_f32_32x32x16_bf16 v[98:113], v[130:133], v[146:149], v[98:113]
	ds_read_b64_tr_b16 v[228:229], v165 offset:0
	ds_read_b64_tr_b16 v[230:231], v165 offset:2048
	ds_read_b64_tr_b16 v[232:233], v216 offset:0
	ds_read_b64_tr_b16 v[234:235], v216 offset:2048
	s_add_i32 s17, s17, 16384
	s_cmp_eq_u32 s17, 114688
	s_cselect_b32 s17, 32768, s17
	v_mfma_f32_32x32x16_bf16 v[98:113], v[134:137], v[142:145], v[98:113]
	ds_read_b64_tr_b16 v[236:237], v217 offset:0
	ds_read_b64_tr_b16 v[238:239], v217 offset:2048
	s_add_i32 s85, s85, 1
	s_cmp_lt_u32 s85, s6
	s_cselect_b32 s8, 0x40000, 0
	v_mfma_f32_32x32x16_bf16 v[98:113], v[184:187], v[138:141], v[98:113]
	s_add_u32 s14, s14, s8
	s_addc_u32 s15, s15, 0
	s_add_u32 s18, s18, s8
	s_addc_u32 s19, s19, 0
	ds_read_b64_tr_b16 v[240:241], v215 offset:4096
	ds_read_b64_tr_b16 v[242:243], v215 offset:6144
	ds_read_b64_tr_b16 v[130:131], v165 offset:4096
	ds_read_b64_tr_b16 v[132:133], v165 offset:6144
	ds_read_b64_tr_b16 v[134:135], v216 offset:4096
	ds_read_b64_tr_b16 v[136:137], v216 offset:6144
	ds_read_b64_tr_b16 v[184:185], v217 offset:4096
	ds_read_b64_tr_b16 v[186:187], v217 offset:6144
	s_cbranch_vccz .Lat_norescale_9
	ds_bpermute_b32 v182, v214, v180
	s_waitcnt lgkmcnt(0)
	v_add_f32_e32 v182, v180, v182
	v_min_f32_e32 v182, 0x7f61b1e6, v182
	v_log_f32_e32 v182, v182
	s_nop 0
	v_floor_f32_e32 v182, v182
	v_max_f32_e32 v182, 0, v182
	v_exp_f32_e64 v183, -v182
	v_add_f32_e32 v80, v80, v182
	v_mul_f32_e32 v81, v81, v183
	v_mul_f32_e32 v180, v180, v183
	v_xor_b32_e32 v64, 0x80000000, v80
	v_mov_b32_e32 v65, v64
	v_mov_b32_e32 v66, v64
	v_mov_b32_e32 v67, v64
	v_mov_b32_e32 v68, v64
	v_mov_b32_e32 v69, v64
	v_mov_b32_e32 v70, v64
	v_mov_b32_e32 v71, v64
	v_mov_b32_e32 v72, v64
	v_mov_b32_e32 v73, v64
	v_mov_b32_e32 v74, v64
	v_mov_b32_e32 v75, v64
	v_mov_b32_e32 v76, v64
	v_mov_b32_e32 v77, v64
	v_mov_b32_e32 v78, v64
	v_mov_b32_e32 v79, v64
	v_sub_f32_e32 v82, v82, v182
	v_sub_f32_e32 v83, v83, v182
	v_sub_f32_e32 v84, v84, v182
	v_sub_f32_e32 v85, v85, v182
	v_sub_f32_e32 v86, v86, v182
	v_sub_f32_e32 v87, v87, v182
	v_sub_f32_e32 v88, v88, v182
	v_sub_f32_e32 v89, v89, v182
	v_sub_f32_e32 v90, v90, v182
	v_sub_f32_e32 v91, v91, v182
	v_sub_f32_e32 v92, v92, v182
	v_sub_f32_e32 v93, v93, v182
	v_sub_f32_e32 v94, v94, v182
	v_sub_f32_e32 v95, v95, v182
	v_sub_f32_e32 v96, v96, v182
	v_sub_f32_e32 v97, v97, v182
	v_sub_f32_e32 v98, v98, v182
	v_sub_f32_e32 v99, v99, v182
	v_sub_f32_e32 v100, v100, v182
	v_sub_f32_e32 v101, v101, v182
	v_sub_f32_e32 v102, v102, v182
	v_sub_f32_e32 v103, v103, v182
	v_sub_f32_e32 v104, v104, v182
	v_sub_f32_e32 v105, v105, v182
	v_sub_f32_e32 v106, v106, v182
	v_sub_f32_e32 v107, v107, v182
	v_sub_f32_e32 v108, v108, v182
	v_sub_f32_e32 v109, v109, v182
	v_sub_f32_e32 v110, v110, v182
	v_sub_f32_e32 v111, v111, v182
	v_sub_f32_e32 v112, v112, v182
	v_sub_f32_e32 v113, v113, v182
	v_mul_f32_e32 v0, v0, v183
	v_mul_f32_e32 v1, v1, v183
	v_mul_f32_e32 v2, v2, v183
	v_mul_f32_e32 v3, v3, v183
	v_mul_f32_e32 v4, v4, v183
	v_mul_f32_e32 v5, v5, v183
	v_mul_f32_e32 v6, v6, v183
	v_mul_f32_e32 v7, v7, v183
	v_mul_f32_e32 v8, v8, v183
	v_mul_f32_e32 v9, v9, v183
	v_mul_f32_e32 v10, v10, v183
	v_mul_f32_e32 v11, v11, v183
	v_mul_f32_e32 v12, v12, v183
	v_mul_f32_e32 v13, v13, v183
	v_mul_f32_e32 v14, v14, v183
	v_mul_f32_e32 v15, v15, v183
	v_mul_f32_e32 v16, v16, v183
	v_mul_f32_e32 v17, v17, v183
	v_mul_f32_e32 v18, v18, v183
	v_mul_f32_e32 v19, v19, v183
	v_mul_f32_e32 v20, v20, v183
	v_mul_f32_e32 v21, v21, v183
	v_mul_f32_e32 v22, v22, v183
	v_mul_f32_e32 v23, v23, v183
	v_mul_f32_e32 v24, v24, v183
	v_mul_f32_e32 v25, v25, v183
	v_mul_f32_e32 v26, v26, v183
	v_mul_f32_e32 v27, v27, v183
	v_mul_f32_e32 v28, v28, v183
	v_mul_f32_e32 v29, v29, v183
	v_mul_f32_e32 v30, v30, v183
	v_mul_f32_e32 v31, v31, v183
	v_mul_f32_e32 v32, v32, v183
	v_mul_f32_e32 v33, v33, v183
	v_mul_f32_e32 v34, v34, v183
	v_mul_f32_e32 v35, v35, v183
	v_mul_f32_e32 v36, v36, v183
	v_mul_f32_e32 v37, v37, v183
	v_mul_f32_e32 v38, v38, v183
	v_mul_f32_e32 v39, v39, v183
	v_mul_f32_e32 v40, v40, v183
	v_mul_f32_e32 v41, v41, v183
	v_mul_f32_e32 v42, v42, v183
	v_mul_f32_e32 v43, v43, v183
	v_mul_f32_e32 v44, v44, v183
	v_mul_f32_e32 v45, v45, v183
	v_mul_f32_e32 v46, v46, v183
	v_mul_f32_e32 v47, v47, v183
	v_mul_f32_e32 v48, v48, v183
	v_mul_f32_e32 v49, v49, v183
	v_mul_f32_e32 v50, v50, v183
	v_mul_f32_e32 v51, v51, v183
	v_mul_f32_e32 v52, v52, v183
	v_mul_f32_e32 v53, v53, v183
	v_mul_f32_e32 v54, v54, v183
	v_mul_f32_e32 v55, v55, v183
	v_mul_f32_e32 v56, v56, v183
	v_mul_f32_e32 v57, v57, v183
	v_mul_f32_e32 v58, v58, v183
	v_mul_f32_e32 v59, v59, v183
	v_mul_f32_e32 v60, v60, v183
	v_mul_f32_e32 v61, v61, v183
	v_mul_f32_e32 v62, v62, v183
	v_mul_f32_e32 v63, v63, v183
	v_lshlrev_b32_e32 v181, 16, v114
	v_and_b32_e32 v114, 0xffff0000, v114
	v_mul_f32_e32 v181, v181, v183
	v_mul_f32_e32 v114, v114, v183
	v_cvt_pk_bf16_f32 v114, v181, v114
	v_lshlrev_b32_e32 v181, 16, v115
	v_and_b32_e32 v115, 0xffff0000, v115
	v_mul_f32_e32 v181, v181, v183
	v_mul_f32_e32 v115, v115, v183
	v_cvt_pk_bf16_f32 v115, v181, v115
	v_lshlrev_b32_e32 v181, 16, v116
	v_and_b32_e32 v116, 0xffff0000, v116
	v_mul_f32_e32 v181, v181, v183
	v_mul_f32_e32 v116, v116, v183
	v_cvt_pk_bf16_f32 v116, v181, v116
	v_lshlrev_b32_e32 v181, 16, v117
	v_and_b32_e32 v117, 0xffff0000, v117
	v_mul_f32_e32 v181, v181, v183
	v_mul_f32_e32 v117, v117, v183
	v_cvt_pk_bf16_f32 v117, v181, v117
	v_lshlrev_b32_e32 v181, 16, v118
	v_and_b32_e32 v118, 0xffff0000, v118
	v_mul_f32_e32 v181, v181, v183
	v_mul_f32_e32 v118, v118, v183
	v_cvt_pk_bf16_f32 v118, v181, v118
	v_lshlrev_b32_e32 v181, 16, v119
	v_and_b32_e32 v119, 0xffff0000, v119
	v_mul_f32_e32 v181, v181, v183
	v_mul_f32_e32 v119, v119, v183
	v_cvt_pk_bf16_f32 v119, v181, v119
	v_lshlrev_b32_e32 v181, 16, v120
	v_and_b32_e32 v120, 0xffff0000, v120
	v_mul_f32_e32 v181, v181, v183
	v_mul_f32_e32 v120, v120, v183
	v_cvt_pk_bf16_f32 v120, v181, v120
	v_lshlrev_b32_e32 v181, 16, v121
	v_and_b32_e32 v121, 0xffff0000, v121
	v_mul_f32_e32 v181, v181, v183
	v_mul_f32_e32 v121, v121, v183
	v_cvt_pk_bf16_f32 v121, v181, v121
	v_lshlrev_b32_e32 v181, 16, v122
	v_and_b32_e32 v122, 0xffff0000, v122
	v_mul_f32_e32 v181, v181, v183
	v_mul_f32_e32 v122, v122, v183
	v_cvt_pk_bf16_f32 v122, v181, v122
	v_lshlrev_b32_e32 v181, 16, v123
	v_and_b32_e32 v123, 0xffff0000, v123
	v_mul_f32_e32 v181, v181, v183
	v_mul_f32_e32 v123, v123, v183
	v_cvt_pk_bf16_f32 v123, v181, v123
	v_lshlrev_b32_e32 v181, 16, v124
	v_and_b32_e32 v124, 0xffff0000, v124
	v_mul_f32_e32 v181, v181, v183
	v_mul_f32_e32 v124, v124, v183
	v_cvt_pk_bf16_f32 v124, v181, v124
	v_lshlrev_b32_e32 v181, 16, v125
	v_and_b32_e32 v125, 0xffff0000, v125
	v_mul_f32_e32 v181, v181, v183
	v_mul_f32_e32 v125, v125, v183
	v_cvt_pk_bf16_f32 v125, v181, v125
	v_lshlrev_b32_e32 v181, 16, v126
	v_and_b32_e32 v126, 0xffff0000, v126
	v_mul_f32_e32 v181, v181, v183
	v_mul_f32_e32 v126, v126, v183
	v_cvt_pk_bf16_f32 v126, v181, v126
	v_lshlrev_b32_e32 v181, 16, v127
	v_and_b32_e32 v127, 0xffff0000, v127
	v_mul_f32_e32 v181, v181, v183
	v_mul_f32_e32 v127, v127, v183
	v_cvt_pk_bf16_f32 v127, v181, v127
	v_lshlrev_b32_e32 v181, 16, v128
	v_and_b32_e32 v128, 0xffff0000, v128
	v_mul_f32_e32 v181, v181, v183
	v_mul_f32_e32 v128, v128, v183
	v_cvt_pk_bf16_f32 v128, v181, v128
	v_lshlrev_b32_e32 v181, 16, v129
	v_and_b32_e32 v129, 0xffff0000, v129
	v_mul_f32_e32 v181, v181, v183
	v_mul_f32_e32 v129, v129, v183
	v_cvt_pk_bf16_f32 v129, v181, v129
	s_nop 0
